# lgk
# speedup vs baseline: 1.0189x; 1.0059x over previous
.LBB0_536:
	s_cmp_lt_i32 s10, 8
	s_cselect_b32 s26, s8, s16
	s_cselect_b32 s24, s10, s22
	s_ashr_i32 s27, s26, 31
	s_lshl_b64 s[38:39], s[26:27], 10
	s_add_u32 s9, s28, s38
	s_mov_b32 s7, s17
	s_mov_b32 s19, s11
	s_addc_u32 s11, s29, s39
	s_lshl_b32 s17, s24, 7
	s_ashr_i32 s23, s17, 31
	s_add_u32 s38, s9, s17
	s_addc_u32 s39, s11, s23
	s_ashr_i32 s25, s24, 31
	s_lshl_b64 s[26:27], s[26:27], 5
	s_add_u32 s9, s30, s26
	s_waitcnt vmcnt(2)
	ds_swizzle_b32 v108, v240 offset:24
	ds_swizzle_b32 v109, v241 offset:24
	ds_swizzle_b32 v110, v240 offset:56
	ds_swizzle_b32 v111, v241 offset:56
	ds_swizzle_b32 v92, v240 offset:88
	ds_swizzle_b32 v93, v241 offset:88
	ds_swizzle_b32 v94, v240 offset:120
	ds_swizzle_b32 v95, v241 offset:120
	ds_swizzle_b32 v72, v240 offset:152
	ds_swizzle_b32 v73, v241 offset:152
	ds_swizzle_b32 v74, v240 offset:184
	ds_swizzle_b32 v75, v241 offset:184
	ds_swizzle_b32 v68, v240 offset:216
	ds_swizzle_b32 v69, v241 offset:216
	ds_swizzle_b32 v70, v240 offset:248
	ds_swizzle_b32 v71, v241 offset:248
	s_waitcnt lgkmcnt(12)
	s_nop 0
	v_lshl_or_b32 v76, s24, 21, v154
	s_addc_u32 s11, s31, s27
	s_lshl_b64 s[24:25], s[24:25], 2
	s_add_u32 s26, s9, s24
	s_addc_u32 s27, s11, s25
	s_cmp_lt_i32 s7, 8
	s_waitcnt vmcnt(2)
	v_lshl_add_u32 v77, v108, 7, v76
	s_cselect_b64 s[24:25], -1, 0
	v_lshl_add_u32 v78, v109, 7, v76
	global_load_dwordx4 v[148:151], v77, s[4:5]
	global_load_dwordx4 v[144:147], v78, s[4:5]
	v_lshl_add_u32 v77, v110, 7, v76
	v_lshl_add_u64 v[104:105], s[38:39], 0, v[154:155]
	s_and_b64 s[38:39], s[24:25], exec
	v_lshl_add_u32 v78, v111, 7, v76
	global_load_dwordx4 v[140:143], v77, s[4:5]
	global_load_dwordx4 v[136:139], v78, s[4:5]
	s_waitcnt lgkmcnt(8)
	v_lshl_add_u32 v77, v92, 7, v76
	s_cselect_b32 s38, s19, s16
	v_lshl_add_u32 v78, v93, 7, v76
	global_load_dwordx4 v[132:135], v77, s[4:5]
	global_load_dwordx4 v[128:131], v78, s[4:5]
	v_lshl_add_u32 v77, v94, 7, v76
	s_waitcnt lgkmcnt(4)
	v_lshl_add_u32 v72, v72, 7, v76
	s_ashr_i32 s39, s38, 31
	v_lshl_add_u32 v78, v95, 7, v76
	global_load_dwordx4 v[124:127], v77, s[4:5]
	global_load_dwordx4 v[120:123], v78, s[4:5]
	v_lshl_add_u32 v73, v73, 7, v76
	global_load_dwordx4 v[116:119], v72, s[4:5]
	global_load_dwordx4 v[112:115], v73, s[4:5]
	v_lshl_add_u32 v72, v74, 7, v76
	s_waitcnt lgkmcnt(0)
	s_nop 0
	v_lshl_add_u32 v68, v68, 7, v76
	v_lshl_add_u32 v69, v69, 7, v76
	s_lshl_b64 s[38:39], s[38:39], 9
	v_lshl_add_u32 v73, v75, 7, v76
	global_load_dwordx4 v[100:103], v72, s[4:5]
	global_load_dwordx4 v[96:99], v73, s[4:5]
	global_load_dwordx4 v[88:91], v68, s[4:5]
	global_load_dwordx4 v[84:87], v69, s[4:5]
	v_lshl_add_u32 v68, v70, 7, v76
	v_lshl_add_u32 v69, v71, 7, v76
	s_add_u32 s98, s20, s38
	s_addc_u32 s99, s21, s39
	global_load_dwordx4 v[80:83], v68, s[4:5]
	global_load_dwordx4 v[76:79], v69, s[4:5]
	global_load_dword v160, v155, s[26:27]
	s_nop 0
	global_load_dwordx2 v[240:241], v243, s[98:99]
	s_nop 0
	global_load_dwordx4 v[104:107], v[104:105], off
	s_nop 0
	v_mov_b32_e32 v153, 0
	v_dot4c_i32_i8_e32 v153, v64, v0
	v_mov_b32_e32 v64, 0
	v_dot4c_i32_i8_e32 v64, v60, v0
	v_dot4c_i32_i8_e32 v64, v61, v1
	v_dot4c_i32_i8_e32 v64, v62, v2
	v_dot4c_i32_i8_e32 v64, v63, v3
	v_dot4c_i32_i8_e32 v153, v65, v1
	v_dot4c_i32_i8_e32 v153, v66, v2
	v_dot4c_i32_i8_e32 v153, v67, v3
	v_add_u32_dpp v60, v64, v64 quad_perm:[1,0,3,2] row_mask:0xf bank_mask:0xf bound_ctrl:1
	v_mov_b32_e32 v64, 0
	v_dot4c_i32_i8_e32 v64, v56, v0
	v_mov_b32_e32 v56, 0
	v_dot4c_i32_i8_e32 v56, v52, v0
	v_dot4c_i32_i8_e32 v56, v53, v1
	v_dot4c_i32_i8_e32 v56, v54, v2
	v_dot4c_i32_i8_e32 v56, v55, v3
	v_dot4c_i32_i8_e32 v64, v57, v1
	v_dot4c_i32_i8_e32 v64, v58, v2
	v_dot4c_i32_i8_e32 v64, v59, v3
	v_add_u32_dpp v52, v56, v56 quad_perm:[1,0,3,2] row_mask:0xf bank_mask:0xf bound_ctrl:1
	v_mov_b32_e32 v56, 0
	v_dot4c_i32_i8_e32 v56, v48, v0
	v_mov_b32_e32 v48, 0
	v_dot4c_i32_i8_e32 v48, v44, v0
	v_dot4c_i32_i8_e32 v48, v45, v1
	v_dot4c_i32_i8_e32 v48, v46, v2
	v_dot4c_i32_i8_e32 v48, v47, v3
	v_dot4c_i32_i8_e32 v56, v49, v1
	v_dot4c_i32_i8_e32 v56, v50, v2
	v_dot4c_i32_i8_e32 v56, v51, v3
	v_add_u32_dpp v44, v48, v48 quad_perm:[1,0,3,2] row_mask:0xf bank_mask:0xf bound_ctrl:1
	v_mov_b32_e32 v48, 0
	v_dot4c_i32_i8_e32 v48, v40, v0
	v_mov_b32_e32 v40, 0
	v_dot4c_i32_i8_e32 v40, v36, v0
	v_dot4c_i32_i8_e32 v40, v37, v1
	v_dot4c_i32_i8_e32 v40, v38, v2
	v_dot4c_i32_i8_e32 v40, v39, v3
	v_dot4c_i32_i8_e32 v48, v41, v1
	v_dot4c_i32_i8_e32 v48, v42, v2
	v_dot4c_i32_i8_e32 v48, v43, v3
	v_add_u32_dpp v36, v40, v40 quad_perm:[1,0,3,2] row_mask:0xf bank_mask:0xf bound_ctrl:1
	v_mov_b32_e32 v40, 0
	v_dot4c_i32_i8_e32 v40, v32, v0
	v_mov_b32_e32 v32, 0
	v_dot4c_i32_i8_e32 v32, v28, v0
	v_dot4c_i32_i8_e32 v32, v29, v1
	v_dot4c_i32_i8_e32 v32, v30, v2
	v_dot4c_i32_i8_e32 v32, v31, v3
	v_dot4c_i32_i8_e32 v40, v33, v1
	v_dot4c_i32_i8_e32 v40, v34, v2
	v_dot4c_i32_i8_e32 v40, v35, v3
	v_add_u32_dpp v28, v32, v32 quad_perm:[1,0,3,2] row_mask:0xf bank_mask:0xf bound_ctrl:1
	v_mov_b32_e32 v32, 0
	v_dot4c_i32_i8_e32 v32, v24, v0
	v_mov_b32_e32 v24, 0
	v_dot4c_i32_i8_e32 v24, v20, v0
	v_dot4c_i32_i8_e32 v24, v21, v1
	v_dot4c_i32_i8_e32 v24, v22, v2
	v_dot4c_i32_i8_e32 v24, v23, v3
	v_dot4c_i32_i8_e32 v32, v25, v1
	v_dot4c_i32_i8_e32 v32, v26, v2
	v_dot4c_i32_i8_e32 v32, v27, v3
	v_add_u32_dpp v20, v24, v24 quad_perm:[1,0,3,2] row_mask:0xf bank_mask:0xf bound_ctrl:1
	v_mov_b32_e32 v24, 0
	v_dot4c_i32_i8_e32 v24, v16, v0
	v_mov_b32_e32 v16, 0
	v_dot4c_i32_i8_e32 v16, v12, v0
	v_dot4c_i32_i8_e32 v16, v13, v1
	v_dot4c_i32_i8_e32 v16, v14, v2
	v_dot4c_i32_i8_e32 v16, v15, v3
	v_dot4c_i32_i8_e32 v24, v17, v1
	v_dot4c_i32_i8_e32 v24, v18, v2
	v_dot4c_i32_i8_e32 v24, v19, v3
	v_add_u32_dpp v12, v16, v16 quad_perm:[1,0,3,2] row_mask:0xf bank_mask:0xf bound_ctrl:1
	v_mov_b32_e32 v16, 0
	v_dot4c_i32_i8_e32 v16, v4, v0
	v_mov_b32_e32 v4, 0
	v_dot4c_i32_i8_e32 v4, v8, v0
	v_dot4c_i32_i8_e32 v16, v5, v1
	v_dot4c_i32_i8_e32 v4, v9, v1
	v_dot4c_i32_i8_e32 v16, v6, v2
	v_dot4c_i32_i8_e32 v4, v10, v2
	v_dot4c_i32_i8_e32 v16, v7, v3
	v_dot4c_i32_i8_e32 v4, v11, v3
	v_add_u32_dpp v61, v153, v153 quad_perm:[1,0,3,2] row_mask:0xf bank_mask:0xf bound_ctrl:1
	v_add_u32_dpp v53, v64, v64 quad_perm:[1,0,3,2] row_mask:0xf bank_mask:0xf bound_ctrl:1
	v_add_u32_dpp v45, v56, v56 quad_perm:[1,0,3,2] row_mask:0xf bank_mask:0xf bound_ctrl:1
	v_add_u32_dpp v37, v48, v48 quad_perm:[1,0,3,2] row_mask:0xf bank_mask:0xf bound_ctrl:1
	v_add_u32_dpp v29, v40, v40 quad_perm:[1,0,3,2] row_mask:0xf bank_mask:0xf bound_ctrl:1
	v_add_u32_dpp v21, v32, v32 quad_perm:[1,0,3,2] row_mask:0xf bank_mask:0xf bound_ctrl:1
	v_add_u32_dpp v13, v24, v24 quad_perm:[1,0,3,2] row_mask:0xf bank_mask:0xf bound_ctrl:1
	v_add_u32_dpp v0, v4, v4 quad_perm:[1,0,3,2] row_mask:0xf bank_mask:0xf bound_ctrl:1
	v_add_u32_dpp v1, v16, v16 quad_perm:[1,0,3,2] row_mask:0xf bank_mask:0xf bound_ctrl:1
	v_add_u32_dpp v60, v60, v60 quad_perm:[2,3,0,1] row_mask:0xf bank_mask:0xf bound_ctrl:1
	v_add_u32_dpp v61, v61, v61 quad_perm:[2,3,0,1] row_mask:0xf bank_mask:0xf bound_ctrl:1
	v_add_u32_dpp v52, v52, v52 quad_perm:[2,3,0,1] row_mask:0xf bank_mask:0xf bound_ctrl:1
	v_add_u32_dpp v53, v53, v53 quad_perm:[2,3,0,1] row_mask:0xf bank_mask:0xf bound_ctrl:1
	v_add_u32_dpp v44, v44, v44 quad_perm:[2,3,0,1] row_mask:0xf bank_mask:0xf bound_ctrl:1
	v_add_u32_dpp v46, v45, v45 quad_perm:[2,3,0,1] row_mask:0xf bank_mask:0xf bound_ctrl:1
	v_add_u32_dpp v36, v36, v36 quad_perm:[2,3,0,1] row_mask:0xf bank_mask:0xf bound_ctrl:1
	v_add_u32_dpp v37, v37, v37 quad_perm:[2,3,0,1] row_mask:0xf bank_mask:0xf bound_ctrl:1
	v_add_u32_dpp v28, v28, v28 quad_perm:[2,3,0,1] row_mask:0xf bank_mask:0xf bound_ctrl:1
	v_add_u32_dpp v29, v29, v29 quad_perm:[2,3,0,1] row_mask:0xf bank_mask:0xf bound_ctrl:1
	v_add_u32_dpp v20, v20, v20 quad_perm:[2,3,0,1] row_mask:0xf bank_mask:0xf bound_ctrl:1
	v_add_u32_dpp v21, v21, v21 quad_perm:[2,3,0,1] row_mask:0xf bank_mask:0xf bound_ctrl:1
	v_add_u32_dpp v12, v12, v12 quad_perm:[2,3,0,1] row_mask:0xf bank_mask:0xf bound_ctrl:1
	v_add_u32_dpp v13, v13, v13 quad_perm:[2,3,0,1] row_mask:0xf bank_mask:0xf bound_ctrl:1
	v_add_u32_dpp v0, v0, v0 quad_perm:[2,3,0,1] row_mask:0xf bank_mask:0xf bound_ctrl:1
	v_add_u32_dpp v1, v1, v1 quad_perm:[2,3,0,1] row_mask:0xf bank_mask:0xf bound_ctrl:1
	v_mov_b32_dpp v62, v61 row_half_mirror row_mask:0xf bank_mask:0xf bound_ctrl:1
	v_mov_b32_dpp v63, v60 row_half_mirror row_mask:0xf bank_mask:0xf bound_ctrl:1
	v_mov_b32_dpp v54, v53 row_half_mirror row_mask:0xf bank_mask:0xf bound_ctrl:1
	v_mov_b32_dpp v55, v52 row_half_mirror row_mask:0xf bank_mask:0xf bound_ctrl:1
	v_mov_b32_dpp v47, v46 row_half_mirror row_mask:0xf bank_mask:0xf bound_ctrl:1
	v_mov_b32_dpp v45, v44 row_half_mirror row_mask:0xf bank_mask:0xf bound_ctrl:1
	v_mov_b32_dpp v38, v37 row_half_mirror row_mask:0xf bank_mask:0xf bound_ctrl:1
	v_mov_b32_dpp v39, v36 row_half_mirror row_mask:0xf bank_mask:0xf bound_ctrl:1
	v_mov_b32_dpp v30, v29 row_half_mirror row_mask:0xf bank_mask:0xf bound_ctrl:1
	v_mov_b32_dpp v31, v28 row_half_mirror row_mask:0xf bank_mask:0xf bound_ctrl:1
	v_mov_b32_dpp v22, v21 row_half_mirror row_mask:0xf bank_mask:0xf bound_ctrl:1
	v_mov_b32_dpp v23, v20 row_half_mirror row_mask:0xf bank_mask:0xf bound_ctrl:1
	v_mov_b32_dpp v14, v13 row_half_mirror row_mask:0xf bank_mask:0xf bound_ctrl:1
	v_mov_b32_dpp v15, v12 row_half_mirror row_mask:0xf bank_mask:0xf bound_ctrl:1
	v_mov_b32_dpp v2, v1 row_half_mirror row_mask:0xf bank_mask:0xf bound_ctrl:1
	v_mov_b32_dpp v3, v0 row_half_mirror row_mask:0xf bank_mask:0xf bound_ctrl:1
	s_and_saveexec_b64 s[26:27], s[2:3]
	s_cbranch_execz .LBB0_538
	v_add_u32_e32 v10, v1, v2
	v_add_u32_e32 v11, v0, v3
	v_add_u32_e32 v2, v53, v54
	v_add_u32_e32 v3, v52, v55
	v_add_u32_e32 v0, v61, v62
	v_add_u32_e32 v1, v60, v63
	v_add_u32_e32 v6, v37, v38
	v_add_u32_e32 v7, v36, v39
	v_add_u32_e32 v4, v46, v47
	v_cvt_f32_i32_e32 v1, v1
	v_cvt_f32_i32_e32 v0, v0
	v_cvt_f32_i32_e32 v3, v3
	v_cvt_f32_i32_e32 v2, v2
	v_add_u32_e32 v5, v44, v45
	v_cvt_f32_i32_e32 v5, v5
	v_cvt_f32_i32_e32 v4, v4
	v_cvt_f32_i32_e32 v7, v7
	v_cvt_f32_i32_e32 v6, v6
	v_add_u32_e32 v13, v13, v14
	v_add_u32_e32 v12, v12, v15
	v_add_u32_e32 v8, v21, v22
	v_add_u32_e32 v9, v20, v23
	v_add_u32_e32 v14, v29, v30
	v_add_u32_e32 v15, v28, v31
	v_pk_mul_f32 v[0:1], v[158:159], v[0:1] op_sel_hi:[0,1]
	v_pk_mul_f32 v[2:3], v[158:159], v[2:3] op_sel_hi:[0,1]
	v_cvt_pk_f16_f32 v0, v0, v1
	v_cvt_pk_f16_f32 v1, v2, v3
	v_pk_mul_f32 v[2:3], v[158:159], v[4:5] op_sel_hi:[0,1]
	v_pk_mul_f32 v[4:5], v[158:159], v[6:7] op_sel_hi:[0,1]
	v_cvt_f32_i32_e32 v7, v15
	v_cvt_f32_i32_e32 v6, v14
	v_cvt_f32_i32_e32 v9, v9
	v_cvt_f32_i32_e32 v8, v8
	v_cvt_pk_f16_f32 v2, v2, v3
	v_cvt_pk_f16_f32 v3, v4, v5
	v_pk_mul_f32 v[4:5], v[158:159], v[6:7] op_sel_hi:[0,1]
	v_pk_mul_f32 v[6:7], v[158:159], v[8:9] op_sel_hi:[0,1]
	v_cvt_f32_i32_e32 v9, v12
	v_cvt_f32_i32_e32 v8, v13
	v_cvt_f32_i32_e32 v11, v11
	v_cvt_f32_i32_e32 v10, v10
	s_ashr_i32 s23, s22, 31
	s_ashr_i32 s17, s16, 31
	s_lshl_b64 s[22:23], s[22:23], 22
	s_add_u32 s9, s14, s22
	s_addc_u32 s11, s15, s23
	s_lshl_b64 s[16:17], s[16:17], 8
	v_cvt_pk_f16_f32 v4, v4, v5
	v_cvt_pk_f16_f32 v5, v6, v7
	v_pk_mul_f32 v[6:7], v[158:159], v[8:9] op_sel_hi:[0,1]
	v_pk_mul_f32 v[8:9], v[158:159], v[10:11] op_sel_hi:[0,1]
	s_add_u32 s16, s9, s16
	v_cvt_pk_f16_f32 v6, v6, v7
	v_cvt_pk_f16_f32 v7, v8, v9
	s_addc_u32 s17, s11, s17
	v_lshlrev_b32_e32 v8, 1, v152
	global_store_dwordx4 v8, v[0:3], s[16:17]
	global_store_dwordx4 v8, v[4:7], s[16:17] offset:16
.LBB0_538:
	s_or_b64 exec, exec, s[26:27]
	s_cmp_gt_i32 s10, 7
	s_cbranch_scc1 .LBB0_541
	s_add_i32 s9, s19, s36
	s_cmpk_gt_i32 s9, 0x3fff
	s_cselect_b32 s23, s6, s9
	s_cselect_b32 s9, s33, 0
	s_add_i32 s22, s9, s7
	s_and_b64 s[16:17], s[24:25], exec
	s_cselect_b32 s24, s19, s8
	s_cselect_b32 s16, s7, s10
	s_ashr_i32 s25, s24, 31
	s_lshl_b64 s[26:27], s[24:25], 10
	s_add_u32 s9, s28, s26
	s_addc_u32 s11, s29, s27
	s_lshl_b32 s17, s16, 7
	s_ashr_i32 s27, s17, 31
	s_add_u32 s26, s9, s17
	v_lshl_or_b32 v0, s16, 21, v154
	s_addc_u32 s27, s11, s27
	s_ashr_i32 s17, s16, 31
	s_lshl_b64 s[24:25], s[24:25], 5
	s_waitcnt vmcnt(2)
	ds_swizzle_b32 v108, v240 offset:24
	ds_swizzle_b32 v109, v241 offset:24
	ds_swizzle_b32 v110, v240 offset:56
	ds_swizzle_b32 v111, v241 offset:56
	ds_swizzle_b32 v92, v240 offset:88
	ds_swizzle_b32 v93, v241 offset:88
	ds_swizzle_b32 v94, v240 offset:120
	ds_swizzle_b32 v95, v241 offset:120
	ds_swizzle_b32 v72, v240 offset:152
	ds_swizzle_b32 v73, v241 offset:152
	ds_swizzle_b32 v74, v240 offset:184
	ds_swizzle_b32 v75, v241 offset:184
	ds_swizzle_b32 v68, v240 offset:216
	ds_swizzle_b32 v69, v241 offset:216
	ds_swizzle_b32 v70, v240 offset:248
	ds_swizzle_b32 v71, v241 offset:248
	s_waitcnt lgkmcnt(12)
	s_nop 0
	v_lshl_add_u32 v1, v108, 7, v0
	s_add_u32 s9, s30, s24
	v_lshl_add_u32 v2, v109, 7, v0
	global_load_dwordx4 v[64:67], v1, s[4:5]
	global_load_dwordx4 v[60:63], v2, s[4:5]
	v_lshl_add_u32 v1, v110, 7, v0
	s_addc_u32 s11, s31, s25
	s_lshl_b64 s[16:17], s[16:17], 2
	v_lshl_add_u32 v2, v111, 7, v0
	global_load_dwordx4 v[56:59], v1, s[4:5]
	global_load_dwordx4 v[52:55], v2, s[4:5]
	s_waitcnt lgkmcnt(8)
	v_lshl_add_u32 v1, v92, 7, v0
	s_add_u32 s16, s9, s16
	v_lshl_add_u32 v2, v93, 7, v0
	global_load_dwordx4 v[48:51], v1, s[4:5]
	global_load_dwordx4 v[44:47], v2, s[4:5]
	v_lshl_add_u32 v1, v94, 7, v0
	s_addc_u32 s17, s11, s17
	v_lshl_add_u32 v2, v95, 7, v0
	global_load_dwordx4 v[40:43], v1, s[4:5]
	global_load_dwordx4 v[36:39], v2, s[4:5]
	s_waitcnt lgkmcnt(4)
	v_lshl_add_u32 v1, v72, 7, v0
	s_cmp_lt_i32 s22, 8
	v_lshl_add_u32 v2, v73, 7, v0
	global_load_dwordx4 v[32:35], v1, s[4:5]
	global_load_dwordx4 v[28:31], v2, s[4:5]
	v_lshl_add_u32 v1, v74, 7, v0
	s_cselect_b32 s24, s23, s8
	v_lshl_add_u32 v2, v75, 7, v0
	global_load_dwordx4 v[24:27], v1, s[4:5]
	global_load_dwordx4 v[20:23], v2, s[4:5]
	s_waitcnt lgkmcnt(0)
	s_nop 0
	v_lshl_add_u32 v1, v68, 7, v0
	s_ashr_i32 s25, s24, 31
	v_lshl_add_u32 v2, v69, 7, v0
	global_load_dwordx4 v[16:19], v1, s[4:5]
	global_load_dwordx4 v[12:15], v2, s[4:5]
	v_lshl_add_u32 v1, v70, 7, v0
	v_lshl_add_u32 v0, v71, 7, v0
	s_lshl_b64 s[24:25], s[24:25], 9
	global_load_dwordx4 v[4:7], v1, s[4:5]
	global_load_dwordx4 v[8:11], v0, s[4:5]
	v_lshl_add_u64 v[0:1], s[26:27], 0, v[154:155]
	s_add_u32 s98, s20, s24
	s_addc_u32 s99, s21, s25
	global_load_dword v158, v155, s[16:17]
	global_load_dwordx2 v[240:241], v243, s[98:99]
	s_nop 0
	global_load_dwordx4 v[0:3], v[0:1], off
	s_nop 0
	v_mov_b32_e32 v153, 0
	v_dot4c_i32_i8_e32 v153, v148, v104
	v_mov_b32_e32 v148, 0
	v_dot4c_i32_i8_e32 v148, v144, v104
	v_dot4c_i32_i8_e32 v148, v145, v105
	v_dot4c_i32_i8_e32 v148, v146, v106
	v_dot4c_i32_i8_e32 v148, v147, v107
	v_dot4c_i32_i8_e32 v153, v149, v105
	v_dot4c_i32_i8_e32 v153, v150, v106
	v_dot4c_i32_i8_e32 v153, v151, v107
	v_add_u32_dpp v144, v148, v148 quad_perm:[1,0,3,2] row_mask:0xf bank_mask:0xf bound_ctrl:1
	v_mov_b32_e32 v148, 0
	v_dot4c_i32_i8_e32 v148, v140, v104
	v_mov_b32_e32 v140, 0
	v_dot4c_i32_i8_e32 v140, v136, v104
	v_dot4c_i32_i8_e32 v140, v137, v105
	v_dot4c_i32_i8_e32 v140, v138, v106
	v_dot4c_i32_i8_e32 v140, v139, v107
	v_dot4c_i32_i8_e32 v148, v141, v105
	v_dot4c_i32_i8_e32 v148, v142, v106
	v_dot4c_i32_i8_e32 v148, v143, v107
	v_add_u32_dpp v136, v140, v140 quad_perm:[1,0,3,2] row_mask:0xf bank_mask:0xf bound_ctrl:1
	v_mov_b32_e32 v140, 0
	v_dot4c_i32_i8_e32 v140, v132, v104
	v_mov_b32_e32 v132, 0
	v_dot4c_i32_i8_e32 v132, v128, v104
	v_dot4c_i32_i8_e32 v132, v129, v105
	v_dot4c_i32_i8_e32 v132, v130, v106
	v_dot4c_i32_i8_e32 v132, v131, v107
	v_dot4c_i32_i8_e32 v140, v133, v105
	v_dot4c_i32_i8_e32 v140, v134, v106
	v_dot4c_i32_i8_e32 v140, v135, v107
	v_add_u32_dpp v128, v132, v132 quad_perm:[1,0,3,2] row_mask:0xf bank_mask:0xf bound_ctrl:1
	v_mov_b32_e32 v132, 0
	v_dot4c_i32_i8_e32 v132, v124, v104
	v_mov_b32_e32 v124, 0
	v_dot4c_i32_i8_e32 v124, v120, v104
	v_dot4c_i32_i8_e32 v124, v121, v105
	v_dot4c_i32_i8_e32 v124, v122, v106
	v_dot4c_i32_i8_e32 v124, v123, v107
	v_dot4c_i32_i8_e32 v132, v125, v105
	v_dot4c_i32_i8_e32 v132, v126, v106
	v_dot4c_i32_i8_e32 v132, v127, v107
	v_add_u32_dpp v120, v124, v124 quad_perm:[1,0,3,2] row_mask:0xf bank_mask:0xf bound_ctrl:1
	v_mov_b32_e32 v124, 0
	v_dot4c_i32_i8_e32 v124, v116, v104
	v_mov_b32_e32 v116, 0
	v_dot4c_i32_i8_e32 v116, v112, v104
	v_dot4c_i32_i8_e32 v116, v113, v105
	v_dot4c_i32_i8_e32 v116, v114, v106
	v_dot4c_i32_i8_e32 v116, v115, v107
	v_dot4c_i32_i8_e32 v124, v117, v105
	v_dot4c_i32_i8_e32 v124, v118, v106
	v_dot4c_i32_i8_e32 v124, v119, v107
	v_add_u32_dpp v112, v116, v116 quad_perm:[1,0,3,2] row_mask:0xf bank_mask:0xf bound_ctrl:1
	v_mov_b32_e32 v116, 0
	v_dot4c_i32_i8_e32 v116, v100, v104
	v_mov_b32_e32 v100, 0
	v_dot4c_i32_i8_e32 v100, v96, v104
	v_dot4c_i32_i8_e32 v100, v97, v105
	v_dot4c_i32_i8_e32 v100, v98, v106
	v_dot4c_i32_i8_e32 v100, v99, v107
	v_dot4c_i32_i8_e32 v116, v101, v105
	v_dot4c_i32_i8_e32 v116, v102, v106
	v_dot4c_i32_i8_e32 v116, v103, v107
	v_add_u32_dpp v96, v100, v100 quad_perm:[1,0,3,2] row_mask:0xf bank_mask:0xf bound_ctrl:1
	v_mov_b32_e32 v100, 0
	v_dot4c_i32_i8_e32 v100, v88, v104
	v_mov_b32_e32 v88, 0
	v_dot4c_i32_i8_e32 v88, v84, v104
	v_dot4c_i32_i8_e32 v88, v85, v105
	v_dot4c_i32_i8_e32 v88, v86, v106
	v_dot4c_i32_i8_e32 v88, v87, v107
	v_dot4c_i32_i8_e32 v100, v89, v105
	v_dot4c_i32_i8_e32 v100, v90, v106
	v_dot4c_i32_i8_e32 v100, v91, v107
	v_add_u32_dpp v84, v88, v88 quad_perm:[1,0,3,2] row_mask:0xf bank_mask:0xf bound_ctrl:1
	v_mov_b32_e32 v88, 0
	v_dot4c_i32_i8_e32 v88, v80, v104
	v_mov_b32_e32 v80, 0
	v_dot4c_i32_i8_e32 v80, v76, v104
	v_dot4c_i32_i8_e32 v88, v81, v105
	v_dot4c_i32_i8_e32 v80, v77, v105
	v_dot4c_i32_i8_e32 v88, v82, v106
	v_dot4c_i32_i8_e32 v80, v78, v106
	v_dot4c_i32_i8_e32 v88, v83, v107
	v_dot4c_i32_i8_e32 v80, v79, v107
	v_add_u32_dpp v145, v153, v153 quad_perm:[1,0,3,2] row_mask:0xf bank_mask:0xf bound_ctrl:1
	v_add_u32_dpp v137, v148, v148 quad_perm:[1,0,3,2] row_mask:0xf bank_mask:0xf bound_ctrl:1
	v_add_u32_dpp v129, v140, v140 quad_perm:[1,0,3,2] row_mask:0xf bank_mask:0xf bound_ctrl:1
	v_add_u32_dpp v121, v132, v132 quad_perm:[1,0,3,2] row_mask:0xf bank_mask:0xf bound_ctrl:1
	v_add_u32_dpp v113, v124, v124 quad_perm:[1,0,3,2] row_mask:0xf bank_mask:0xf bound_ctrl:1
	v_add_u32_dpp v97, v116, v116 quad_perm:[1,0,3,2] row_mask:0xf bank_mask:0xf bound_ctrl:1
	v_add_u32_dpp v85, v100, v100 quad_perm:[1,0,3,2] row_mask:0xf bank_mask:0xf bound_ctrl:1
	v_add_u32_dpp v76, v80, v80 quad_perm:[1,0,3,2] row_mask:0xf bank_mask:0xf bound_ctrl:1
	v_add_u32_dpp v77, v88, v88 quad_perm:[1,0,3,2] row_mask:0xf bank_mask:0xf bound_ctrl:1
	v_add_u32_dpp v144, v144, v144 quad_perm:[2,3,0,1] row_mask:0xf bank_mask:0xf bound_ctrl:1
	v_add_u32_dpp v145, v145, v145 quad_perm:[2,3,0,1] row_mask:0xf bank_mask:0xf bound_ctrl:1
	v_add_u32_dpp v136, v136, v136 quad_perm:[2,3,0,1] row_mask:0xf bank_mask:0xf bound_ctrl:1
	v_add_u32_dpp v137, v137, v137 quad_perm:[2,3,0,1] row_mask:0xf bank_mask:0xf bound_ctrl:1
	v_add_u32_dpp v128, v128, v128 quad_perm:[2,3,0,1] row_mask:0xf bank_mask:0xf bound_ctrl:1
	v_add_u32_dpp v130, v129, v129 quad_perm:[2,3,0,1] row_mask:0xf bank_mask:0xf bound_ctrl:1
	v_add_u32_dpp v120, v120, v120 quad_perm:[2,3,0,1] row_mask:0xf bank_mask:0xf bound_ctrl:1
	v_add_u32_dpp v121, v121, v121 quad_perm:[2,3,0,1] row_mask:0xf bank_mask:0xf bound_ctrl:1
	v_add_u32_dpp v112, v112, v112 quad_perm:[2,3,0,1] row_mask:0xf bank_mask:0xf bound_ctrl:1
	v_add_u32_dpp v113, v113, v113 quad_perm:[2,3,0,1] row_mask:0xf bank_mask:0xf bound_ctrl:1
	v_add_u32_dpp v96, v96, v96 quad_perm:[2,3,0,1] row_mask:0xf bank_mask:0xf bound_ctrl:1
	v_add_u32_dpp v97, v97, v97 quad_perm:[2,3,0,1] row_mask:0xf bank_mask:0xf bound_ctrl:1
	v_add_u32_dpp v84, v84, v84 quad_perm:[2,3,0,1] row_mask:0xf bank_mask:0xf bound_ctrl:1
	v_add_u32_dpp v85, v85, v85 quad_perm:[2,3,0,1] row_mask:0xf bank_mask:0xf bound_ctrl:1
	v_add_u32_dpp v76, v76, v76 quad_perm:[2,3,0,1] row_mask:0xf bank_mask:0xf bound_ctrl:1
	v_add_u32_dpp v77, v77, v77 quad_perm:[2,3,0,1] row_mask:0xf bank_mask:0xf bound_ctrl:1
	v_mov_b32_dpp v146, v145 row_half_mirror row_mask:0xf bank_mask:0xf bound_ctrl:1
	v_mov_b32_dpp v147, v144 row_half_mirror row_mask:0xf bank_mask:0xf bound_ctrl:1
	v_mov_b32_dpp v138, v137 row_half_mirror row_mask:0xf bank_mask:0xf bound_ctrl:1
	v_mov_b32_dpp v139, v136 row_half_mirror row_mask:0xf bank_mask:0xf bound_ctrl:1
	v_mov_b32_dpp v131, v130 row_half_mirror row_mask:0xf bank_mask:0xf bound_ctrl:1
	v_mov_b32_dpp v129, v128 row_half_mirror row_mask:0xf bank_mask:0xf bound_ctrl:1
	v_mov_b32_dpp v122, v121 row_half_mirror row_mask:0xf bank_mask:0xf bound_ctrl:1
	v_mov_b32_dpp v123, v120 row_half_mirror row_mask:0xf bank_mask:0xf bound_ctrl:1
	v_mov_b32_dpp v114, v113 row_half_mirror row_mask:0xf bank_mask:0xf bound_ctrl:1
	v_mov_b32_dpp v115, v112 row_half_mirror row_mask:0xf bank_mask:0xf bound_ctrl:1
	v_mov_b32_dpp v98, v97 row_half_mirror row_mask:0xf bank_mask:0xf bound_ctrl:1
	v_mov_b32_dpp v99, v96 row_half_mirror row_mask:0xf bank_mask:0xf bound_ctrl:1
	v_mov_b32_dpp v86, v85 row_half_mirror row_mask:0xf bank_mask:0xf bound_ctrl:1
	v_mov_b32_dpp v87, v84 row_half_mirror row_mask:0xf bank_mask:0xf bound_ctrl:1
	v_mov_b32_dpp v78, v77 row_half_mirror row_mask:0xf bank_mask:0xf bound_ctrl:1
	v_mov_b32_dpp v79, v76 row_half_mirror row_mask:0xf bank_mask:0xf bound_ctrl:1
	s_and_saveexec_b64 s[16:17], s[2:3]
	s_cbranch_execz .LBB0_534
	v_add_u32_e32 v88, v77, v78
	v_add_u32_e32 v89, v76, v79
	v_add_u32_e32 v78, v137, v138
	v_add_u32_e32 v79, v136, v139
	v_add_u32_e32 v76, v145, v146
	v_add_u32_e32 v77, v144, v147
	v_add_u32_e32 v82, v121, v122
	v_add_u32_e32 v83, v120, v123
	v_add_u32_e32 v80, v130, v131
	v_cvt_f32_i32_e32 v77, v77
	v_cvt_f32_i32_e32 v76, v76
	v_cvt_f32_i32_e32 v79, v79
	v_cvt_f32_i32_e32 v78, v78
	v_add_u32_e32 v81, v128, v129
	v_cvt_f32_i32_e32 v81, v81
	v_cvt_f32_i32_e32 v80, v80
	v_cvt_f32_i32_e32 v83, v83
	v_cvt_f32_i32_e32 v82, v82
	v_add_u32_e32 v86, v85, v86
	v_add_u32_e32 v87, v84, v87
	v_add_u32_e32 v84, v97, v98
	v_add_u32_e32 v85, v96, v99
	v_add_u32_e32 v90, v113, v114
	v_add_u32_e32 v91, v112, v115
	v_pk_mul_f32 v[76:77], v[160:161], v[76:77] op_sel_hi:[0,1]
	v_pk_mul_f32 v[78:79], v[160:161], v[78:79] op_sel_hi:[0,1]
	v_cvt_pk_f16_f32 v76, v76, v77
	v_cvt_pk_f16_f32 v77, v78, v79
	v_pk_mul_f32 v[78:79], v[160:161], v[80:81] op_sel_hi:[0,1]
	v_pk_mul_f32 v[80:81], v[160:161], v[82:83] op_sel_hi:[0,1]
	v_cvt_f32_i32_e32 v83, v91
	v_cvt_f32_i32_e32 v82, v90
	v_cvt_f32_i32_e32 v85, v85
	v_cvt_f32_i32_e32 v84, v84
	v_cvt_pk_f16_f32 v78, v78, v79
	v_cvt_pk_f16_f32 v79, v80, v81
	v_pk_mul_f32 v[80:81], v[160:161], v[82:83] op_sel_hi:[0,1]
	v_pk_mul_f32 v[82:83], v[160:161], v[84:85] op_sel_hi:[0,1]
	v_cvt_f32_i32_e32 v85, v87
	v_cvt_f32_i32_e32 v84, v86
	v_cvt_f32_i32_e32 v87, v89
	v_cvt_f32_i32_e32 v86, v88
	s_ashr_i32 s11, s10, 31
	s_ashr_i32 s9, s8, 31
	s_lshl_b64 s[10:11], s[10:11], 22
	s_add_u32 s10, s14, s10
	s_addc_u32 s11, s15, s11
	s_lshl_b64 s[8:9], s[8:9], 8
	v_cvt_pk_f16_f32 v80, v80, v81
	v_cvt_pk_f16_f32 v81, v82, v83
	v_pk_mul_f32 v[82:83], v[160:161], v[84:85] op_sel_hi:[0,1]
	v_pk_mul_f32 v[84:85], v[160:161], v[86:87] op_sel_hi:[0,1]
	s_add_u32 s8, s10, s8
	v_cvt_pk_f16_f32 v82, v82, v83
	v_cvt_pk_f16_f32 v83, v84, v85
	s_addc_u32 s9, s11, s9
	v_lshlrev_b32_e32 v84, 1, v152
	global_store_dwordx4 v84, v[76:79], s[8:9]
	global_store_dwordx4 v84, v[80:83], s[8:9] offset:16
	s_branch .LBB0_534

.LBB0_622:
	s_mov_b32 s9, s18
	s_cmp_lt_i32 s22, 8
	s_cselect_b32 s17, s22, s9
	s_waitcnt vmcnt(1)
	ds_swizzle_b32 v140, v250 offset:24
	ds_swizzle_b32 v141, v251 offset:24
	ds_swizzle_b32 v142, v250 offset:56
	ds_swizzle_b32 v143, v251 offset:56
	ds_swizzle_b32 v132, v250 offset:88
	ds_swizzle_b32 v133, v251 offset:88
	ds_swizzle_b32 v134, v250 offset:120
	ds_swizzle_b32 v135, v251 offset:120
	ds_swizzle_b32 v108, v250 offset:152
	ds_swizzle_b32 v109, v251 offset:152
	ds_swizzle_b32 v110, v250 offset:184
	ds_swizzle_b32 v111, v251 offset:184
	ds_swizzle_b32 v100, v250 offset:216
	ds_swizzle_b32 v101, v251 offset:216
	ds_swizzle_b32 v102, v250 offset:248
	ds_swizzle_b32 v103, v251 offset:248
	s_waitcnt lgkmcnt(12)
	s_nop 0
	v_lshl_or_b32 v80, s17, 21, v196
	s_waitcnt vmcnt(1)
	v_lshl_add_u32 v81, v140, 7, v80
	v_lshl_add_u32 v82, v141, 7, v80
	s_mov_b32 s16, s23
	global_load_dwordx4 v[168:171], v81, s[4:5]
	global_load_dwordx4 v[164:167], v82, s[4:5]
	v_lshl_add_u32 v81, v142, 7, v80
	v_lshl_add_u32 v82, v143, 7, v80
	global_load_dwordx4 v[160:163], v81, s[4:5]
	global_load_dwordx4 v[156:159], v82, s[4:5]
	s_waitcnt lgkmcnt(8)
	v_lshl_add_u32 v81, v132, 7, v80
	v_lshl_add_u32 v82, v133, 7, v80
	s_cselect_b32 s20, s8, s16
	global_load_dwordx4 v[152:155], v81, s[4:5]
	global_load_dwordx4 v[144:147], v82, s[4:5]
	v_lshl_add_u32 v81, v134, 7, v80
	v_lshl_add_u32 v82, v135, 7, v80
	s_ashr_i32 s21, s20, 31
	global_load_dwordx4 v[136:139], v81, s[4:5]
	global_load_dwordx4 v[128:131], v82, s[4:5]
	s_waitcnt lgkmcnt(4)
	v_lshl_add_u32 v81, v108, 7, v80
	v_lshl_add_u32 v82, v109, 7, v80
	s_lshl_b64 s[20:21], s[20:21], 9
	global_load_dwordx4 v[124:127], v81, s[4:5]
	global_load_dwordx4 v[120:123], v82, s[4:5]
	v_lshl_add_u32 v81, v110, 7, v80
	v_lshl_add_u32 v82, v111, 7, v80
	s_cmp_lt_i32 s27, 8
	global_load_dwordx4 v[112:115], v81, s[4:5]
	global_load_dwordx4 v[104:107], v82, s[4:5]
	s_waitcnt lgkmcnt(0)
	s_nop 0
	v_lshl_add_u32 v81, v100, 7, v80
	v_lshl_add_u32 v82, v101, 7, v80
	v_lshl_add_u64 v[100:101], v[244:245], 0, s[20:21]
	s_cselect_b64 s[20:21], -1, 0
	s_and_b64 s[24:25], s[20:21], exec
	s_cselect_b32 s24, s26, s16
	s_ashr_i32 s25, s24, 31
	global_load_dwordx4 v[96:99], v81, s[4:5]
	global_load_dwordx4 v[92:95], v82, s[4:5]
	v_lshl_add_u32 v81, v102, 7, v80
	v_lshl_add_u32 v80, v103, 7, v80
	s_lshl_b64 s[24:25], s[24:25], 9
	global_load_dwordx4 v[88:91], v81, s[4:5]
	s_nop 0
	global_load_dwordx4 v[80:83], v80, s[4:5]
	s_nop 0
	ds_swizzle_b32 v60, v248 offset:24
	ds_swizzle_b32 v61, v249 offset:24
	ds_swizzle_b32 v62, v248 offset:56
	ds_swizzle_b32 v63, v249 offset:56
	ds_swizzle_b32 v36, v248 offset:88
	ds_swizzle_b32 v37, v249 offset:88
	ds_swizzle_b32 v38, v248 offset:120
	ds_swizzle_b32 v39, v249 offset:120
	ds_swizzle_b32 v12, v248 offset:152
	ds_swizzle_b32 v13, v249 offset:152
	ds_swizzle_b32 v14, v248 offset:184
	ds_swizzle_b32 v15, v249 offset:184
	ds_swizzle_b32 v0, v248 offset:216
	ds_swizzle_b32 v1, v249 offset:216
	ds_swizzle_b32 v2, v248 offset:248
	ds_swizzle_b32 v3, v249 offset:248
	global_load_dwordx2 v[248:249], v[100:101], off
	v_lshl_add_u64 v[100:101], v[246:247], 0, s[24:25]
	global_load_dwordx2 v[250:251], v[100:101], off
	s_waitcnt lgkmcnt(0)
	s_nop 0
	v_cvt_scalef32_pk_f16_fp8 v100, v76, 1.0
	v_cvt_scalef32_pk_f16_fp8 v76, v76, 1.0 op_sel:[1,0,0]
	v_cvt_scalef32_pk_f16_fp8 v101, v77, 1.0
	v_cvt_scalef32_pk_f16_fp8 v77, v77, 1.0 op_sel:[1,0,0]
	v_cvt_scalef32_pk_f16_fp8 v102, v78, 1.0
	v_cvt_scalef32_pk_f16_fp8 v78, v78, 1.0 op_sel:[1,0,0]
	v_cvt_scalef32_pk_f16_fp8 v103, v79, 1.0
	v_cvt_scalef32_pk_f16_fp8 v79, v79, 1.0 op_sel:[1,0,0]
	v_pk_fma_f16 v100, v100, v60, 0
	v_pk_fma_f16 v76, v76, v60, 0
	v_pk_fma_f16 v101, v101, v60, 0
	v_pk_fma_f16 v77, v77, v60, 0
	v_pk_fma_f16 v102, v102, v60, 0
	v_pk_fma_f16 v78, v78, v60, 0
	v_pk_fma_f16 v103, v103, v60, 0
	v_pk_fma_f16 v60, v79, v60, 0
	v_cvt_scalef32_pk_f16_fp8 v79, v72, 1.0
	v_cvt_scalef32_pk_f16_fp8 v72, v72, 1.0 op_sel:[1,0,0]
	v_pk_fma_f16 v72, v72, v61, v76
	v_cvt_scalef32_pk_f16_fp8 v76, v73, 1.0
	v_cvt_scalef32_pk_f16_fp8 v73, v73, 1.0 op_sel:[1,0,0]
	v_pk_fma_f16 v73, v73, v61, v77
	v_cvt_scalef32_pk_f16_fp8 v77, v74, 1.0
	v_cvt_scalef32_pk_f16_fp8 v74, v74, 1.0 op_sel:[1,0,0]
	v_pk_fma_f16 v74, v74, v61, v78
	v_cvt_scalef32_pk_f16_fp8 v78, v75, 1.0
	v_cvt_scalef32_pk_f16_fp8 v75, v75, 1.0 op_sel:[1,0,0]
	v_pk_fma_f16 v79, v79, v61, v100
	v_pk_fma_f16 v76, v76, v61, v101
	v_pk_fma_f16 v77, v77, v61, v102
	v_pk_fma_f16 v78, v78, v61, v103
	v_pk_fma_f16 v60, v75, v61, v60
	v_cvt_scalef32_pk_f16_fp8 v61, v68, 1.0
	v_cvt_scalef32_pk_f16_fp8 v68, v68, 1.0 op_sel:[1,0,0]
	v_pk_fma_f16 v68, v68, v62, v72
	v_cvt_scalef32_pk_f16_fp8 v72, v69, 1.0
	v_cvt_scalef32_pk_f16_fp8 v69, v69, 1.0 op_sel:[1,0,0]
	v_pk_fma_f16 v69, v69, v62, v73
	v_cvt_scalef32_pk_f16_fp8 v73, v70, 1.0
	v_cvt_scalef32_pk_f16_fp8 v70, v70, 1.0 op_sel:[1,0,0]
	v_pk_fma_f16 v70, v70, v62, v74
	v_cvt_scalef32_pk_f16_fp8 v74, v71, 1.0
	v_cvt_scalef32_pk_f16_fp8 v71, v71, 1.0 op_sel:[1,0,0]
	v_pk_fma_f16 v61, v61, v62, v79
	v_pk_fma_f16 v72, v72, v62, v76
	v_pk_fma_f16 v73, v73, v62, v77
	v_pk_fma_f16 v74, v74, v62, v78
	v_pk_fma_f16 v60, v71, v62, v60
	v_cvt_scalef32_pk_f16_fp8 v62, v64, 1.0
	v_pk_fma_f16 v61, v62, v63, v61
	v_cvt_scalef32_pk_f16_fp8 v62, v64, 1.0 op_sel:[1,0,0]
	v_cvt_scalef32_pk_f16_fp8 v64, v65, 1.0
	v_cvt_scalef32_pk_f16_fp8 v65, v65, 1.0 op_sel:[1,0,0]
	v_pk_fma_f16 v62, v62, v63, v68
	v_pk_fma_f16 v65, v65, v63, v69
	v_cvt_scalef32_pk_f16_fp8 v68, v66, 1.0
	v_cvt_scalef32_pk_f16_fp8 v66, v66, 1.0 op_sel:[1,0,0]
	v_cvt_scalef32_pk_f16_fp8 v69, v67, 1.0
	v_cvt_scalef32_pk_f16_fp8 v67, v67, 1.0 op_sel:[1,0,0]
	v_pk_fma_f16 v64, v64, v63, v72
	v_pk_fma_f16 v68, v68, v63, v73
	v_pk_fma_f16 v66, v66, v63, v70
	v_pk_fma_f16 v69, v69, v63, v74
	v_pk_fma_f16 v60, v67, v63, v60
	v_cvt_scalef32_pk_f16_fp8 v63, v56, 1.0
	v_cvt_scalef32_pk_f16_fp8 v56, v56, 1.0 op_sel:[1,0,0]
	v_pk_fma_f16 v56, v56, v36, v62
	v_cvt_scalef32_pk_f16_fp8 v62, v57, 1.0
	v_pk_fma_f16 v61, v63, v36, v61
	v_pk_fma_f16 v62, v62, v36, v64
	v_cvt_scalef32_pk_f16_fp8 v57, v57, 1.0 op_sel:[1,0,0]
	v_cvt_scalef32_pk_f16_fp8 v63, v58, 1.0
	v_cvt_scalef32_pk_f16_fp8 v58, v58, 1.0 op_sel:[1,0,0]
	v_cvt_scalef32_pk_f16_fp8 v64, v59, 1.0
	v_cvt_scalef32_pk_f16_fp8 v59, v59, 1.0 op_sel:[1,0,0]
	v_pk_fma_f16 v57, v57, v36, v65
	v_pk_fma_f16 v63, v63, v36, v68
	v_pk_fma_f16 v58, v58, v36, v66
	v_pk_fma_f16 v64, v64, v36, v69
	v_pk_fma_f16 v36, v59, v36, v60
	v_cvt_scalef32_pk_f16_fp8 v59, v52, 1.0
	v_cvt_scalef32_pk_f16_fp8 v52, v52, 1.0 op_sel:[1,0,0]
	v_pk_fma_f16 v52, v52, v37, v56
	v_cvt_scalef32_pk_f16_fp8 v56, v53, 1.0
	v_cvt_scalef32_pk_f16_fp8 v53, v53, 1.0 op_sel:[1,0,0]
	v_pk_fma_f16 v53, v53, v37, v57
	v_cvt_scalef32_pk_f16_fp8 v57, v54, 1.0
	v_cvt_scalef32_pk_f16_fp8 v54, v54, 1.0 op_sel:[1,0,0]
	v_pk_fma_f16 v54, v54, v37, v58
	v_cvt_scalef32_pk_f16_fp8 v58, v55, 1.0
	v_cvt_scalef32_pk_f16_fp8 v55, v55, 1.0 op_sel:[1,0,0]
	v_pk_fma_f16 v59, v59, v37, v61
	v_pk_fma_f16 v56, v56, v37, v62
	v_pk_fma_f16 v57, v57, v37, v63
	v_pk_fma_f16 v58, v58, v37, v64
	v_pk_fma_f16 v36, v55, v37, v36
	v_cvt_scalef32_pk_f16_fp8 v37, v48, 1.0
	v_cvt_scalef32_pk_f16_fp8 v48, v48, 1.0 op_sel:[1,0,0]
	v_pk_fma_f16 v48, v48, v38, v52
	v_cvt_scalef32_pk_f16_fp8 v52, v49, 1.0
	v_cvt_scalef32_pk_f16_fp8 v49, v49, 1.0 op_sel:[1,0,0]
	v_pk_fma_f16 v49, v49, v38, v53
	v_cvt_scalef32_pk_f16_fp8 v53, v50, 1.0
	v_cvt_scalef32_pk_f16_fp8 v50, v50, 1.0 op_sel:[1,0,0]
	v_pk_fma_f16 v50, v50, v38, v54
	v_cvt_scalef32_pk_f16_fp8 v54, v51, 1.0
	v_cvt_scalef32_pk_f16_fp8 v51, v51, 1.0 op_sel:[1,0,0]
	v_pk_fma_f16 v37, v37, v38, v59
	v_pk_fma_f16 v52, v52, v38, v56
	v_pk_fma_f16 v53, v53, v38, v57
	v_pk_fma_f16 v54, v54, v38, v58
	v_pk_fma_f16 v36, v51, v38, v36
	v_cvt_scalef32_pk_f16_fp8 v38, v44, 1.0
	v_pk_fma_f16 v37, v38, v39, v37
	v_cvt_scalef32_pk_f16_fp8 v38, v44, 1.0 op_sel:[1,0,0]
	v_cvt_scalef32_pk_f16_fp8 v44, v45, 1.0
	v_cvt_scalef32_pk_f16_fp8 v45, v45, 1.0 op_sel:[1,0,0]
	v_pk_fma_f16 v38, v38, v39, v48
	v_pk_fma_f16 v45, v45, v39, v49
	v_cvt_scalef32_pk_f16_fp8 v48, v46, 1.0
	v_cvt_scalef32_pk_f16_fp8 v46, v46, 1.0 op_sel:[1,0,0]
	v_cvt_scalef32_pk_f16_fp8 v49, v47, 1.0
	v_cvt_scalef32_pk_f16_fp8 v47, v47, 1.0 op_sel:[1,0,0]
	v_pk_fma_f16 v44, v44, v39, v52
	v_pk_fma_f16 v48, v48, v39, v53
	v_pk_fma_f16 v46, v46, v39, v50
	v_pk_fma_f16 v49, v49, v39, v54
	v_pk_fma_f16 v36, v47, v39, v36
	v_cvt_scalef32_pk_f16_fp8 v39, v40, 1.0
	v_pk_fma_f16 v37, v39, v12, v37
	v_cvt_scalef32_pk_f16_fp8 v39, v40, 1.0 op_sel:[1,0,0]
	v_pk_fma_f16 v38, v39, v12, v38
	v_cvt_scalef32_pk_f16_fp8 v39, v41, 1.0
	v_pk_fma_f16 v39, v39, v12, v44
	v_cvt_scalef32_pk_f16_fp8 v40, v41, 1.0 op_sel:[1,0,0]
	v_cvt_scalef32_pk_f16_fp8 v41, v42, 1.0
	v_cvt_scalef32_pk_f16_fp8 v42, v42, 1.0 op_sel:[1,0,0]
	v_cvt_scalef32_pk_f16_fp8 v44, v43, 1.0
	v_cvt_scalef32_pk_f16_fp8 v43, v43, 1.0 op_sel:[1,0,0]
	v_pk_fma_f16 v40, v40, v12, v45
	v_pk_fma_f16 v41, v41, v12, v48
	v_pk_fma_f16 v42, v42, v12, v46
	v_pk_fma_f16 v44, v44, v12, v49
	v_pk_fma_f16 v12, v43, v12, v36
	v_cvt_scalef32_pk_f16_fp8 v36, v32, 1.0
	v_pk_fma_f16 v36, v36, v13, v37
	v_cvt_scalef32_pk_f16_fp8 v32, v32, 1.0 op_sel:[1,0,0]
	v_cvt_scalef32_pk_f16_fp8 v37, v33, 1.0
	v_pk_fma_f16 v32, v32, v13, v38
	v_pk_fma_f16 v37, v37, v13, v39
	v_cvt_scalef32_pk_f16_fp8 v33, v33, 1.0 op_sel:[1,0,0]
	v_cvt_scalef32_pk_f16_fp8 v38, v34, 1.0
	v_cvt_scalef32_pk_f16_fp8 v34, v34, 1.0 op_sel:[1,0,0]
	v_cvt_scalef32_pk_f16_fp8 v39, v35, 1.0
	v_cvt_scalef32_pk_f16_fp8 v35, v35, 1.0 op_sel:[1,0,0]
	v_pk_fma_f16 v33, v33, v13, v40
	v_pk_fma_f16 v38, v38, v13, v41
	v_pk_fma_f16 v34, v34, v13, v42
	v_pk_fma_f16 v39, v39, v13, v44
	v_pk_fma_f16 v12, v35, v13, v12
	v_cvt_scalef32_pk_f16_fp8 v13, v28, 1.0
	v_cvt_scalef32_pk_f16_fp8 v28, v28, 1.0 op_sel:[1,0,0]
	v_pk_fma_f16 v28, v28, v14, v32
	v_cvt_scalef32_pk_f16_fp8 v32, v29, 1.0
	v_cvt_scalef32_pk_f16_fp8 v29, v29, 1.0 op_sel:[1,0,0]
	v_pk_fma_f16 v29, v29, v14, v33
	v_cvt_scalef32_pk_f16_fp8 v33, v30, 1.0
	v_cvt_scalef32_pk_f16_fp8 v30, v30, 1.0 op_sel:[1,0,0]
	v_pk_fma_f16 v30, v30, v14, v34
	v_cvt_scalef32_pk_f16_fp8 v34, v31, 1.0
	v_cvt_scalef32_pk_f16_fp8 v31, v31, 1.0 op_sel:[1,0,0]
	v_pk_fma_f16 v13, v13, v14, v36
	v_pk_fma_f16 v32, v32, v14, v37
	v_pk_fma_f16 v33, v33, v14, v38
	v_pk_fma_f16 v34, v34, v14, v39
	v_pk_fma_f16 v12, v31, v14, v12
	v_cvt_scalef32_pk_f16_fp8 v14, v24, 1.0
	v_pk_fma_f16 v13, v14, v15, v13
	v_cvt_scalef32_pk_f16_fp8 v14, v24, 1.0 op_sel:[1,0,0]
	v_cvt_scalef32_pk_f16_fp8 v24, v25, 1.0
	v_cvt_scalef32_pk_f16_fp8 v25, v25, 1.0 op_sel:[1,0,0]
	v_pk_fma_f16 v14, v14, v15, v28
	v_pk_fma_f16 v25, v25, v15, v29
	v_cvt_scalef32_pk_f16_fp8 v28, v26, 1.0
	v_cvt_scalef32_pk_f16_fp8 v26, v26, 1.0 op_sel:[1,0,0]
	v_cvt_scalef32_pk_f16_fp8 v29, v27, 1.0
	v_cvt_scalef32_pk_f16_fp8 v27, v27, 1.0 op_sel:[1,0,0]
	v_pk_fma_f16 v24, v24, v15, v32
	v_pk_fma_f16 v28, v28, v15, v33
	v_pk_fma_f16 v26, v26, v15, v30
	v_pk_fma_f16 v29, v29, v15, v34
	v_pk_fma_f16 v12, v27, v15, v12
	v_cvt_scalef32_pk_f16_fp8 v15, v20, 1.0
	v_pk_fma_f16 v13, v15, v0, v13
	v_cvt_scalef32_pk_f16_fp8 v15, v20, 1.0 op_sel:[1,0,0]
	v_pk_fma_f16 v14, v15, v0, v14
	v_cvt_scalef32_pk_f16_fp8 v15, v21, 1.0
	v_pk_fma_f16 v15, v15, v0, v24
	v_cvt_scalef32_pk_f16_fp8 v20, v21, 1.0 op_sel:[1,0,0]
	v_cvt_scalef32_pk_f16_fp8 v21, v22, 1.0
	v_cvt_scalef32_pk_f16_fp8 v22, v22, 1.0 op_sel:[1,0,0]
	v_cvt_scalef32_pk_f16_fp8 v24, v23, 1.0
	v_cvt_scalef32_pk_f16_fp8 v23, v23, 1.0 op_sel:[1,0,0]
	v_pk_fma_f16 v20, v20, v0, v25
	v_pk_fma_f16 v21, v21, v0, v28
	v_pk_fma_f16 v22, v22, v0, v26
	v_pk_fma_f16 v24, v24, v0, v29
	v_pk_fma_f16 v0, v23, v0, v12
	v_cvt_scalef32_pk_f16_fp8 v12, v16, 1.0
	v_pk_fma_f16 v12, v12, v1, v13
	v_cvt_scalef32_pk_f16_fp8 v13, v16, 1.0 op_sel:[1,0,0]
	v_pk_fma_f16 v13, v13, v1, v14
	v_cvt_scalef32_pk_f16_fp8 v14, v17, 1.0
	v_pk_fma_f16 v14, v14, v1, v15
	v_cvt_scalef32_pk_f16_fp8 v15, v17, 1.0 op_sel:[1,0,0]
	v_cvt_scalef32_pk_f16_fp8 v16, v18, 1.0
	v_cvt_scalef32_pk_f16_fp8 v17, v18, 1.0 op_sel:[1,0,0]
	v_cvt_scalef32_pk_f16_fp8 v18, v19, 1.0
	v_cvt_scalef32_pk_f16_fp8 v19, v19, 1.0 op_sel:[1,0,0]
	v_pk_fma_f16 v15, v15, v1, v20
	v_pk_fma_f16 v16, v16, v1, v21
	v_pk_fma_f16 v17, v17, v1, v22
	v_pk_fma_f16 v18, v18, v1, v24
	v_pk_fma_f16 v0, v19, v1, v0
	v_cvt_scalef32_pk_f16_fp8 v1, v4, 1.0
	v_pk_fma_f16 v1, v1, v2, v12
	v_cvt_scalef32_pk_f16_fp8 v4, v4, 1.0 op_sel:[1,0,0]
	v_cvt_scalef32_pk_f16_fp8 v12, v5, 1.0
	v_pk_fma_f16 v4, v4, v2, v13
	v_pk_fma_f16 v12, v12, v2, v14
	v_cvt_scalef32_pk_f16_fp8 v5, v5, 1.0 op_sel:[1,0,0]
	v_cvt_scalef32_pk_f16_fp8 v13, v6, 1.0
	v_cvt_scalef32_pk_f16_fp8 v6, v6, 1.0 op_sel:[1,0,0]
	v_cvt_scalef32_pk_f16_fp8 v14, v7, 1.0
	v_cvt_scalef32_pk_f16_fp8 v7, v7, 1.0 op_sel:[1,0,0]
	v_pk_fma_f16 v5, v5, v2, v15
	v_pk_fma_f16 v13, v13, v2, v16
	v_pk_fma_f16 v6, v6, v2, v17
	v_pk_fma_f16 v14, v14, v2, v18
	v_pk_fma_f16 v0, v7, v2, v0
	v_cvt_scalef32_pk_f16_fp8 v2, v8, 1.0
	v_pk_fma_f16 v1, v2, v3, v1
	v_cvt_scalef32_pk_f16_fp8 v2, v8, 1.0 op_sel:[1,0,0]
	v_cvt_scalef32_pk_f16_fp8 v7, v9, 1.0 op_sel:[1,0,0]
	v_cvt_scalef32_pk_f16_fp8 v8, v10, 1.0 op_sel:[1,0,0]
	v_pk_fma_f16 v2, v2, v3, v4
	v_cvt_scalef32_pk_f16_fp8 v4, v9, 1.0
	v_pk_fma_f16 v5, v7, v3, v5
	v_cvt_scalef32_pk_f16_fp8 v7, v10, 1.0
	v_pk_fma_f16 v6, v8, v3, v6
	v_cvt_scalef32_pk_f16_fp8 v8, v11, 1.0
	v_cvt_scalef32_pk_f16_fp8 v9, v11, 1.0 op_sel:[1,0,0]
	v_pk_fma_f16 v4, v4, v3, v12
	v_pk_fma_f16 v7, v7, v3, v13
	v_pk_fma_f16 v8, v8, v3, v14
	v_pk_fma_f16 v0, v9, v3, v0
	v_permlane32_swap_b32_e32 v1, v7
	v_permlane32_swap_b32_e32 v2, v6
	v_permlane32_swap_b32_e32 v4, v8
	v_permlane32_swap_b32_e32 v5, v0
	v_pk_add_f16 v1, v1, v7
	v_pk_add_f16 v2, v2, v6
	v_pk_add_f16 v3, v4, v8
	v_pk_add_f16 v0, v5, v0
	s_nop 0
	v_permlane16_swap_b32_e32 v1, v3
	v_permlane16_swap_b32_e32 v2, v0
	v_pk_add_f16 v1, v1, v3
	v_pk_add_f16 v0, v2, v0
	s_ashr_i32 s17, s16, 31
	v_cndmask_b32_e64 v2, v1, v0, s[2:3]
	v_cndmask_b32_e64 v0, v0, v1, s[2:3]
	s_lshl_b64 s[16:17], s[16:17], 11
	v_mov_b32_dpp v1, v2 row_ror:8 row_mask:0xf bank_mask:0xf bound_ctrl:1
	v_pk_add_f16 v1, v1, v0
	s_add_u32 s24, s14, s16
	v_cvt_f32_f16_e32 v0, v1
	v_cvt_f32_f16_sdwa v1, v1 dst_sel:DWORD dst_unused:UNUSED_PAD src0_sel:WORD_1
	s_addc_u32 s25, s15, s17
	s_lshl_b32 s16, s9, 7
	s_ashr_i32 s17, s16, 31
	v_pk_mul_f32 v[0:1], v[0:1], s[10:11] op_sel_hi:[1,0]
	s_lshl_b64 s[16:17], s[16:17], 1
	v_and_b32_sdwa v3, v0, v208 dst_sel:DWORD dst_unused:UNUSED_PAD src0_sel:WORD_1 src1_sel:DWORD
	v_and_b32_sdwa v2, v1, v208 dst_sel:DWORD dst_unused:UNUSED_PAD src0_sel:WORD_1 src1_sel:DWORD
	v_add3_u32 v0, v0, v3, s7
	s_add_u32 s16, s24, s16
	v_add3_u32 v1, v1, v2, s7
	v_lshrrev_b32_e32 v0, 16, v0
	s_addc_u32 s17, s25, s17
	v_and_or_b32 v2, v1, s11, v0
	v_lshl_add_u64 v[0:1], s[16:17], 0, v[194:195]
	s_mov_b32 s18, s27
	s_mov_b32 s23, s26
	v_lshl_add_u64 v[0:1], v[0:1], 0, v[204:205]
	s_cmp_gt_i32 s22, 7
	s_mov_b64 s[16:17], -1
	global_store_dword v[0:1], v2, off
	s_cbranch_scc1 .LBB0_621
	s_add_i32 s9, s23, s19
	s_cmpk_gt_i32 s9, 0x3fff
	s_cselect_b32 s25, s33, 0
	s_cselect_b32 s24, s6, s9
	s_add_i32 s25, s25, s18
	s_and_b64 s[16:17], s[20:21], exec
	s_cselect_b32 s9, s18, s22
	v_lshl_or_b32 v0, s9, 21, v196
	s_waitcnt vmcnt(1)
	ds_swizzle_b32 v188, v250 offset:24
	ds_swizzle_b32 v189, v251 offset:24
	ds_swizzle_b32 v190, v250 offset:56
	ds_swizzle_b32 v191, v251 offset:56
	ds_swizzle_b32 v184, v250 offset:88
	ds_swizzle_b32 v185, v251 offset:88
	ds_swizzle_b32 v186, v250 offset:120
	ds_swizzle_b32 v187, v251 offset:120
	ds_swizzle_b32 v180, v250 offset:152
	ds_swizzle_b32 v181, v251 offset:152
	ds_swizzle_b32 v182, v250 offset:184
	ds_swizzle_b32 v183, v251 offset:184
	ds_swizzle_b32 v176, v250 offset:216
	ds_swizzle_b32 v177, v251 offset:216
	ds_swizzle_b32 v178, v250 offset:248
	ds_swizzle_b32 v179, v251 offset:248
	s_waitcnt lgkmcnt(12)
	s_nop 0
	v_lshl_add_u32 v1, v188, 7, v0
	s_cselect_b32 s16, s23, s8
	v_lshl_add_u32 v2, v189, 7, v0
	global_load_dwordx4 v[76:79], v1, s[4:5]
	global_load_dwordx4 v[72:75], v2, s[4:5]
	v_lshl_add_u32 v1, v190, 7, v0
	s_ashr_i32 s17, s16, 31
	v_lshl_add_u32 v2, v191, 7, v0
	global_load_dwordx4 v[68:71], v1, s[4:5]
	global_load_dwordx4 v[64:67], v2, s[4:5]
	s_waitcnt lgkmcnt(8)
	v_lshl_add_u32 v1, v184, 7, v0
	s_lshl_b64 s[16:17], s[16:17], 9
	v_lshl_add_u32 v2, v185, 7, v0
	global_load_dwordx4 v[56:59], v1, s[4:5]
	global_load_dwordx4 v[52:55], v2, s[4:5]
	v_lshl_add_u32 v1, v186, 7, v0
	s_cmp_lt_i32 s25, 8
	v_lshl_add_u32 v2, v187, 7, v0
	global_load_dwordx4 v[48:51], v1, s[4:5]
	global_load_dwordx4 v[44:47], v2, s[4:5]
	s_waitcnt lgkmcnt(4)
	v_lshl_add_u32 v1, v180, 7, v0
	v_lshl_add_u64 v[60:61], v[244:245], 0, s[16:17]
	s_cselect_b32 s16, s24, s8
	v_lshl_add_u32 v2, v181, 7, v0
	global_load_dwordx4 v[40:43], v1, s[4:5]
	global_load_dwordx4 v[32:35], v2, s[4:5]
	v_lshl_add_u32 v1, v182, 7, v0
	s_ashr_i32 s17, s16, 31
	v_lshl_add_u32 v2, v183, 7, v0
	global_load_dwordx4 v[28:31], v1, s[4:5]
	global_load_dwordx4 v[24:27], v2, s[4:5]
	s_waitcnt lgkmcnt(0)
	s_nop 0
	v_lshl_add_u32 v1, v176, 7, v0
	s_lshl_b64 s[16:17], s[16:17], 9
	v_lshl_add_u32 v2, v177, 7, v0
	global_load_dwordx4 v[20:23], v1, s[4:5]
	global_load_dwordx4 v[16:19], v2, s[4:5]
	v_lshl_add_u32 v1, v178, 7, v0
	v_lshl_add_u32 v0, v179, 7, v0
	v_lshl_add_u64 v[140:141], v[246:247], 0, s[16:17]
	global_load_dwordx4 v[4:7], v1, s[4:5]
	global_load_dwordx4 v[8:11], v0, s[4:5]
	s_nop 0
	ds_swizzle_b32 v172, v248 offset:24
	ds_swizzle_b32 v173, v249 offset:24
	ds_swizzle_b32 v174, v248 offset:56
	ds_swizzle_b32 v175, v249 offset:56
	ds_swizzle_b32 v148, v248 offset:88
	ds_swizzle_b32 v149, v249 offset:88
	ds_swizzle_b32 v150, v248 offset:120
	ds_swizzle_b32 v151, v249 offset:120
	ds_swizzle_b32 v116, v248 offset:152
	ds_swizzle_b32 v117, v249 offset:152
	ds_swizzle_b32 v118, v248 offset:184
	ds_swizzle_b32 v119, v249 offset:184
	ds_swizzle_b32 v84, v248 offset:216
	ds_swizzle_b32 v85, v249 offset:216
	ds_swizzle_b32 v86, v248 offset:248
	ds_swizzle_b32 v87, v249 offset:248
	global_load_dwordx2 v[248:249], v[60:61], off
	s_nop 0
	global_load_dwordx2 v[250:251], v[140:141], off
	s_waitcnt lgkmcnt(0)
	s_nop 0
	v_cvt_scalef32_pk_f16_fp8 v176, v168, 1.0
	v_cvt_scalef32_pk_f16_fp8 v168, v168, 1.0 op_sel:[1,0,0]
	v_cvt_scalef32_pk_f16_fp8 v177, v169, 1.0
	v_cvt_scalef32_pk_f16_fp8 v169, v169, 1.0 op_sel:[1,0,0]
	v_cvt_scalef32_pk_f16_fp8 v178, v170, 1.0
	v_cvt_scalef32_pk_f16_fp8 v170, v170, 1.0 op_sel:[1,0,0]
	v_cvt_scalef32_pk_f16_fp8 v179, v171, 1.0
	v_cvt_scalef32_pk_f16_fp8 v171, v171, 1.0 op_sel:[1,0,0]
	v_pk_fma_f16 v176, v176, v172, 0
	v_pk_fma_f16 v168, v168, v172, 0
	v_pk_fma_f16 v177, v177, v172, 0
	v_pk_fma_f16 v169, v169, v172, 0
	v_pk_fma_f16 v178, v178, v172, 0
	v_pk_fma_f16 v170, v170, v172, 0
	v_pk_fma_f16 v179, v179, v172, 0
	v_pk_fma_f16 v171, v171, v172, 0
	v_cvt_scalef32_pk_f16_fp8 v172, v164, 1.0
	v_cvt_scalef32_pk_f16_fp8 v164, v164, 1.0 op_sel:[1,0,0]
	v_pk_fma_f16 v164, v164, v173, v168
	v_cvt_scalef32_pk_f16_fp8 v168, v165, 1.0
	v_cvt_scalef32_pk_f16_fp8 v165, v165, 1.0 op_sel:[1,0,0]
	v_pk_fma_f16 v165, v165, v173, v169
	v_cvt_scalef32_pk_f16_fp8 v169, v166, 1.0
	v_cvt_scalef32_pk_f16_fp8 v166, v166, 1.0 op_sel:[1,0,0]
	v_pk_fma_f16 v166, v166, v173, v170
	v_cvt_scalef32_pk_f16_fp8 v170, v167, 1.0
	v_cvt_scalef32_pk_f16_fp8 v167, v167, 1.0 op_sel:[1,0,0]
	v_pk_fma_f16 v167, v167, v173, v171
	v_cvt_scalef32_pk_f16_fp8 v171, v160, 1.0
	v_cvt_scalef32_pk_f16_fp8 v160, v160, 1.0 op_sel:[1,0,0]
	v_pk_fma_f16 v160, v160, v174, v164
	v_cvt_scalef32_pk_f16_fp8 v164, v161, 1.0
	v_cvt_scalef32_pk_f16_fp8 v161, v161, 1.0 op_sel:[1,0,0]
	v_pk_fma_f16 v161, v161, v174, v165
	v_cvt_scalef32_pk_f16_fp8 v165, v162, 1.0
	v_cvt_scalef32_pk_f16_fp8 v162, v162, 1.0 op_sel:[1,0,0]
	v_pk_fma_f16 v162, v162, v174, v166
	v_cvt_scalef32_pk_f16_fp8 v166, v163, 1.0
	v_cvt_scalef32_pk_f16_fp8 v163, v163, 1.0 op_sel:[1,0,0]
	v_pk_fma_f16 v163, v163, v174, v167
	v_cvt_scalef32_pk_f16_fp8 v167, v156, 1.0
	v_cvt_scalef32_pk_f16_fp8 v156, v156, 1.0 op_sel:[1,0,0]
	v_pk_fma_f16 v156, v156, v175, v160
	v_cvt_scalef32_pk_f16_fp8 v160, v157, 1.0
	v_cvt_scalef32_pk_f16_fp8 v157, v157, 1.0 op_sel:[1,0,0]
	v_pk_fma_f16 v157, v157, v175, v161
	v_cvt_scalef32_pk_f16_fp8 v161, v158, 1.0
	v_cvt_scalef32_pk_f16_fp8 v158, v158, 1.0 op_sel:[1,0,0]
	v_pk_fma_f16 v158, v158, v175, v162
	v_cvt_scalef32_pk_f16_fp8 v162, v159, 1.0
	v_cvt_scalef32_pk_f16_fp8 v159, v159, 1.0 op_sel:[1,0,0]
	v_pk_fma_f16 v159, v159, v175, v163
	v_cvt_scalef32_pk_f16_fp8 v163, v152, 1.0
	v_cvt_scalef32_pk_f16_fp8 v152, v152, 1.0 op_sel:[1,0,0]
	v_pk_fma_f16 v172, v172, v173, v176
	v_pk_fma_f16 v168, v168, v173, v177
	v_pk_fma_f16 v169, v169, v173, v178
	v_pk_fma_f16 v170, v170, v173, v179
	v_pk_fma_f16 v152, v152, v148, v156
	v_cvt_scalef32_pk_f16_fp8 v156, v153, 1.0
	v_cvt_scalef32_pk_f16_fp8 v153, v153, 1.0 op_sel:[1,0,0]
	v_pk_fma_f16 v171, v171, v174, v172
	v_pk_fma_f16 v164, v164, v174, v168
	v_pk_fma_f16 v165, v165, v174, v169
	v_pk_fma_f16 v166, v166, v174, v170
	v_pk_fma_f16 v153, v153, v148, v157
	v_cvt_scalef32_pk_f16_fp8 v157, v154, 1.0
	v_cvt_scalef32_pk_f16_fp8 v154, v154, 1.0 op_sel:[1,0,0]
	v_pk_fma_f16 v167, v167, v175, v171
	v_pk_fma_f16 v160, v160, v175, v164
	v_pk_fma_f16 v161, v161, v175, v165
	v_pk_fma_f16 v162, v162, v175, v166
	v_pk_fma_f16 v154, v154, v148, v158
	v_cvt_scalef32_pk_f16_fp8 v158, v155, 1.0
	v_cvt_scalef32_pk_f16_fp8 v155, v155, 1.0 op_sel:[1,0,0]
	v_pk_fma_f16 v163, v163, v148, v167
	v_pk_fma_f16 v156, v156, v148, v160
	v_pk_fma_f16 v157, v157, v148, v161
	v_pk_fma_f16 v158, v158, v148, v162
	v_pk_fma_f16 v148, v155, v148, v159
	v_cvt_scalef32_pk_f16_fp8 v155, v144, 1.0
	v_cvt_scalef32_pk_f16_fp8 v144, v144, 1.0 op_sel:[1,0,0]
	v_pk_fma_f16 v144, v144, v149, v152
	v_cvt_scalef32_pk_f16_fp8 v152, v145, 1.0
	v_cvt_scalef32_pk_f16_fp8 v145, v145, 1.0 op_sel:[1,0,0]
	v_pk_fma_f16 v145, v145, v149, v153
	v_cvt_scalef32_pk_f16_fp8 v153, v146, 1.0
	v_cvt_scalef32_pk_f16_fp8 v146, v146, 1.0 op_sel:[1,0,0]
	v_pk_fma_f16 v146, v146, v149, v154
	v_cvt_scalef32_pk_f16_fp8 v154, v147, 1.0
	v_cvt_scalef32_pk_f16_fp8 v147, v147, 1.0 op_sel:[1,0,0]
	v_pk_fma_f16 v147, v147, v149, v148
	v_cvt_scalef32_pk_f16_fp8 v148, v136, 1.0
	v_cvt_scalef32_pk_f16_fp8 v136, v136, 1.0 op_sel:[1,0,0]
	v_pk_fma_f16 v136, v136, v150, v144
	v_cvt_scalef32_pk_f16_fp8 v144, v137, 1.0
	v_cvt_scalef32_pk_f16_fp8 v137, v137, 1.0 op_sel:[1,0,0]
	v_pk_fma_f16 v137, v137, v150, v145
	v_cvt_scalef32_pk_f16_fp8 v145, v138, 1.0
	v_cvt_scalef32_pk_f16_fp8 v138, v138, 1.0 op_sel:[1,0,0]
	v_pk_fma_f16 v138, v138, v150, v146
	v_cvt_scalef32_pk_f16_fp8 v146, v139, 1.0
	v_cvt_scalef32_pk_f16_fp8 v139, v139, 1.0 op_sel:[1,0,0]
	v_pk_fma_f16 v139, v139, v150, v147
	v_cvt_scalef32_pk_f16_fp8 v147, v128, 1.0
	v_cvt_scalef32_pk_f16_fp8 v128, v128, 1.0 op_sel:[1,0,0]
	v_pk_fma_f16 v128, v128, v151, v136
	v_cvt_scalef32_pk_f16_fp8 v136, v129, 1.0
	v_cvt_scalef32_pk_f16_fp8 v129, v129, 1.0 op_sel:[1,0,0]
	v_pk_fma_f16 v129, v129, v151, v137
	v_cvt_scalef32_pk_f16_fp8 v137, v130, 1.0
	v_cvt_scalef32_pk_f16_fp8 v130, v130, 1.0 op_sel:[1,0,0]
	v_pk_fma_f16 v130, v130, v151, v138
	v_cvt_scalef32_pk_f16_fp8 v138, v131, 1.0
	v_cvt_scalef32_pk_f16_fp8 v131, v131, 1.0 op_sel:[1,0,0]
	v_pk_fma_f16 v131, v131, v151, v139
	v_cvt_scalef32_pk_f16_fp8 v139, v124, 1.0
	v_cvt_scalef32_pk_f16_fp8 v124, v124, 1.0 op_sel:[1,0,0]
	v_pk_fma_f16 v155, v155, v149, v163
	v_pk_fma_f16 v152, v152, v149, v156
	v_pk_fma_f16 v153, v153, v149, v157
	v_pk_fma_f16 v154, v154, v149, v158
	v_pk_fma_f16 v124, v124, v116, v128
	v_cvt_scalef32_pk_f16_fp8 v128, v125, 1.0
	v_cvt_scalef32_pk_f16_fp8 v125, v125, 1.0 op_sel:[1,0,0]
	v_pk_fma_f16 v148, v148, v150, v155
	v_pk_fma_f16 v144, v144, v150, v152
	v_pk_fma_f16 v145, v145, v150, v153
	v_pk_fma_f16 v146, v146, v150, v154
	v_pk_fma_f16 v125, v125, v116, v129
	v_cvt_scalef32_pk_f16_fp8 v129, v126, 1.0
	v_cvt_scalef32_pk_f16_fp8 v126, v126, 1.0 op_sel:[1,0,0]
	v_pk_fma_f16 v147, v147, v151, v148
	v_pk_fma_f16 v136, v136, v151, v144
	v_pk_fma_f16 v137, v137, v151, v145
	v_pk_fma_f16 v138, v138, v151, v146
	v_pk_fma_f16 v126, v126, v116, v130
	v_cvt_scalef32_pk_f16_fp8 v130, v127, 1.0
	v_cvt_scalef32_pk_f16_fp8 v127, v127, 1.0 op_sel:[1,0,0]
	v_pk_fma_f16 v139, v139, v116, v147
	v_pk_fma_f16 v128, v128, v116, v136
	v_pk_fma_f16 v129, v129, v116, v137
	v_pk_fma_f16 v130, v130, v116, v138
	v_pk_fma_f16 v116, v127, v116, v131
	v_cvt_scalef32_pk_f16_fp8 v127, v120, 1.0
	v_cvt_scalef32_pk_f16_fp8 v120, v120, 1.0 op_sel:[1,0,0]
	v_pk_fma_f16 v120, v120, v117, v124
	v_cvt_scalef32_pk_f16_fp8 v124, v121, 1.0
	v_cvt_scalef32_pk_f16_fp8 v121, v121, 1.0 op_sel:[1,0,0]
	v_pk_fma_f16 v121, v121, v117, v125
	v_cvt_scalef32_pk_f16_fp8 v125, v122, 1.0
	v_cvt_scalef32_pk_f16_fp8 v122, v122, 1.0 op_sel:[1,0,0]
	v_pk_fma_f16 v122, v122, v117, v126
	v_cvt_scalef32_pk_f16_fp8 v126, v123, 1.0
	v_cvt_scalef32_pk_f16_fp8 v123, v123, 1.0 op_sel:[1,0,0]
	v_pk_fma_f16 v127, v127, v117, v139
	v_pk_fma_f16 v124, v124, v117, v128
	v_pk_fma_f16 v125, v125, v117, v129
	v_pk_fma_f16 v126, v126, v117, v130
	v_pk_fma_f16 v116, v123, v117, v116
	v_cvt_scalef32_pk_f16_fp8 v117, v112, 1.0
	v_cvt_scalef32_pk_f16_fp8 v112, v112, 1.0 op_sel:[1,0,0]
	v_pk_fma_f16 v112, v112, v118, v120
	v_cvt_scalef32_pk_f16_fp8 v120, v113, 1.0
	v_cvt_scalef32_pk_f16_fp8 v113, v113, 1.0 op_sel:[1,0,0]
	v_pk_fma_f16 v113, v113, v118, v121
	v_cvt_scalef32_pk_f16_fp8 v121, v114, 1.0
	v_cvt_scalef32_pk_f16_fp8 v114, v114, 1.0 op_sel:[1,0,0]
	v_pk_fma_f16 v114, v114, v118, v122
	v_cvt_scalef32_pk_f16_fp8 v122, v115, 1.0
	v_cvt_scalef32_pk_f16_fp8 v115, v115, 1.0 op_sel:[1,0,0]
	v_pk_fma_f16 v115, v115, v118, v116
	v_cvt_scalef32_pk_f16_fp8 v116, v104, 1.0
	v_cvt_scalef32_pk_f16_fp8 v104, v104, 1.0 op_sel:[1,0,0]
	v_pk_fma_f16 v104, v104, v119, v112
	v_cvt_scalef32_pk_f16_fp8 v112, v105, 1.0
	v_cvt_scalef32_pk_f16_fp8 v105, v105, 1.0 op_sel:[1,0,0]
	v_pk_fma_f16 v105, v105, v119, v113
	v_cvt_scalef32_pk_f16_fp8 v113, v106, 1.0
	v_cvt_scalef32_pk_f16_fp8 v106, v106, 1.0 op_sel:[1,0,0]
	v_pk_fma_f16 v106, v106, v119, v114
	v_cvt_scalef32_pk_f16_fp8 v114, v107, 1.0
	v_cvt_scalef32_pk_f16_fp8 v107, v107, 1.0 op_sel:[1,0,0]
	v_pk_fma_f16 v107, v107, v119, v115
	v_cvt_scalef32_pk_f16_fp8 v115, v96, 1.0
	v_cvt_scalef32_pk_f16_fp8 v96, v96, 1.0 op_sel:[1,0,0]
	v_pk_fma_f16 v96, v96, v84, v104
	v_cvt_scalef32_pk_f16_fp8 v104, v97, 1.0
	v_cvt_scalef32_pk_f16_fp8 v97, v97, 1.0 op_sel:[1,0,0]
	v_pk_fma_f16 v117, v117, v118, v127
	v_pk_fma_f16 v120, v120, v118, v124
	v_pk_fma_f16 v121, v121, v118, v125
	v_pk_fma_f16 v122, v122, v118, v126
	v_pk_fma_f16 v97, v97, v84, v105
	v_cvt_scalef32_pk_f16_fp8 v105, v98, 1.0
	v_cvt_scalef32_pk_f16_fp8 v98, v98, 1.0 op_sel:[1,0,0]
	v_pk_fma_f16 v116, v116, v119, v117
	v_pk_fma_f16 v112, v112, v119, v120
	v_pk_fma_f16 v113, v113, v119, v121
	v_pk_fma_f16 v114, v114, v119, v122
	v_pk_fma_f16 v98, v98, v84, v106
	v_cvt_scalef32_pk_f16_fp8 v106, v99, 1.0
	v_cvt_scalef32_pk_f16_fp8 v99, v99, 1.0 op_sel:[1,0,0]
	v_pk_fma_f16 v115, v115, v84, v116
	v_pk_fma_f16 v104, v104, v84, v112
	v_pk_fma_f16 v105, v105, v84, v113
	v_pk_fma_f16 v106, v106, v84, v114
	v_pk_fma_f16 v84, v99, v84, v107
	v_cvt_scalef32_pk_f16_fp8 v99, v92, 1.0
	v_cvt_scalef32_pk_f16_fp8 v92, v92, 1.0 op_sel:[1,0,0]
	v_pk_fma_f16 v92, v92, v85, v96
	v_cvt_scalef32_pk_f16_fp8 v96, v93, 1.0
	v_cvt_scalef32_pk_f16_fp8 v93, v93, 1.0 op_sel:[1,0,0]
	v_pk_fma_f16 v93, v93, v85, v97
	v_cvt_scalef32_pk_f16_fp8 v97, v94, 1.0
	v_cvt_scalef32_pk_f16_fp8 v94, v94, 1.0 op_sel:[1,0,0]
	v_pk_fma_f16 v94, v94, v85, v98
	v_cvt_scalef32_pk_f16_fp8 v98, v95, 1.0
	v_cvt_scalef32_pk_f16_fp8 v95, v95, 1.0 op_sel:[1,0,0]
	v_pk_fma_f16 v99, v99, v85, v115
	v_pk_fma_f16 v96, v96, v85, v104
	v_pk_fma_f16 v97, v97, v85, v105
	v_pk_fma_f16 v98, v98, v85, v106
	v_pk_fma_f16 v84, v95, v85, v84
	v_cvt_scalef32_pk_f16_fp8 v85, v88, 1.0
	v_cvt_scalef32_pk_f16_fp8 v88, v88, 1.0 op_sel:[1,0,0]
	v_pk_fma_f16 v88, v88, v86, v92
	v_cvt_scalef32_pk_f16_fp8 v92, v89, 1.0
	v_cvt_scalef32_pk_f16_fp8 v89, v89, 1.0 op_sel:[1,0,0]
	v_pk_fma_f16 v89, v89, v86, v93
	v_cvt_scalef32_pk_f16_fp8 v93, v90, 1.0
	v_cvt_scalef32_pk_f16_fp8 v90, v90, 1.0 op_sel:[1,0,0]
	v_pk_fma_f16 v90, v90, v86, v94
	v_cvt_scalef32_pk_f16_fp8 v94, v91, 1.0
	v_cvt_scalef32_pk_f16_fp8 v91, v91, 1.0 op_sel:[1,0,0]
	v_pk_fma_f16 v85, v85, v86, v99
	v_pk_fma_f16 v92, v92, v86, v96
	v_pk_fma_f16 v93, v93, v86, v97
	v_pk_fma_f16 v94, v94, v86, v98
	v_pk_fma_f16 v84, v91, v86, v84
	v_cvt_scalef32_pk_f16_fp8 v86, v80, 1.0
	v_pk_fma_f16 v85, v86, v87, v85
	v_cvt_scalef32_pk_f16_fp8 v80, v80, 1.0 op_sel:[1,0,0]
	v_cvt_scalef32_pk_f16_fp8 v86, v81, 1.0
	v_cvt_scalef32_pk_f16_fp8 v81, v81, 1.0 op_sel:[1,0,0]
	v_pk_fma_f16 v80, v80, v87, v88
	v_pk_fma_f16 v81, v81, v87, v89
	v_cvt_scalef32_pk_f16_fp8 v88, v82, 1.0
	v_cvt_scalef32_pk_f16_fp8 v82, v82, 1.0 op_sel:[1,0,0]
	v_cvt_scalef32_pk_f16_fp8 v89, v83, 1.0
	v_cvt_scalef32_pk_f16_fp8 v83, v83, 1.0 op_sel:[1,0,0]
	v_pk_fma_f16 v86, v86, v87, v92
	v_pk_fma_f16 v88, v88, v87, v93
	v_pk_fma_f16 v82, v82, v87, v90
	v_pk_fma_f16 v89, v89, v87, v94
	v_pk_fma_f16 v83, v83, v87, v84
	v_permlane32_swap_b32_e32 v85, v88
	v_permlane32_swap_b32_e32 v80, v82
	v_permlane32_swap_b32_e32 v86, v89
	v_permlane32_swap_b32_e32 v81, v83
	v_pk_add_f16 v84, v85, v88
	v_pk_add_f16 v80, v80, v82
	v_pk_add_f16 v82, v86, v89
	v_pk_add_f16 v81, v81, v83
	s_nop 0
	v_permlane16_swap_b32_e32 v84, v82
	v_permlane16_swap_b32_e32 v80, v81
	v_pk_add_f16 v82, v84, v82
	v_pk_add_f16 v80, v80, v81
	s_ashr_i32 s9, s8, 31
	v_cndmask_b32_e64 v81, v82, v80, s[2:3]
	v_cndmask_b32_e64 v80, v80, v82, s[2:3]
	s_lshl_b64 s[8:9], s[8:9], 11
	v_mov_b32_dpp v81, v81 row_ror:8 row_mask:0xf bank_mask:0xf bound_ctrl:1
	v_pk_add_f16 v81, v81, v80
	s_add_u32 s16, s14, s8
	v_cvt_f32_f16_e32 v80, v81
	v_cvt_f32_f16_sdwa v81, v81 dst_sel:DWORD dst_unused:UNUSED_PAD src0_sel:WORD_1
	s_addc_u32 s17, s15, s9
	s_lshl_b32 s8, s22, 7
	s_ashr_i32 s9, s8, 31
	v_pk_mul_f32 v[80:81], v[80:81], s[10:11] op_sel_hi:[1,0]
	s_lshl_b64 s[8:9], s[8:9], 1
	v_and_b32_sdwa v83, v80, v208 dst_sel:DWORD dst_unused:UNUSED_PAD src0_sel:WORD_1 src1_sel:DWORD
	v_and_b32_sdwa v82, v81, v208 dst_sel:DWORD dst_unused:UNUSED_PAD src0_sel:WORD_1 src1_sel:DWORD
	v_add3_u32 v80, v80, v83, s7
	s_add_u32 s8, s16, s8
	v_add3_u32 v81, v81, v82, s7
	v_lshrrev_b32_e32 v80, 16, v80
	s_addc_u32 s9, s17, s9
	v_and_or_b32 v82, v81, s11, v80
	v_lshl_add_u64 v[80:81], s[8:9], 0, v[194:195]
	s_add_i32 s8, s24, s19
	s_cmpk_gt_i32 s8, 0x3fff
	s_cselect_b32 s26, s6, s8
	s_cselect_b32 s8, s33, 0
	s_add_i32 s27, s8, s25
	v_mov_b32_e32 v203, v195
	s_cmp_gt_i32 s18, 7
	v_lshl_add_u64 v[80:81], v[80:81], 0, v[202:203]
	s_cselect_b64 s[16:17], -1, 0
	s_mov_b32 s22, s25
	s_mov_b32 s8, s24
	global_store_dword v[80:81], v82, off
	s_branch .LBB0_621
